# GQA and MLA attention loops: packed f32 row-sum adds split into plain v_add_f32 pairs
# speedup vs baseline: 1.0313x; 1.0057x over previous
.LBB0_134:
	v_exp_f32_e32 v228, v96
	v_exp_f32_e32 v112, v112
	v_exp_f32_e32 v96, v113
	v_exp_f32_e32 v113, v97
	v_exp_f32_e32 v233, v98
	v_exp_f32_e32 v114, v114
	v_add_f32_e32 v229, 0, v228
	v_exp_f32_e32 v98, v115
	v_add_f32_e32 v97, 0, v112
	v_add_f32_e32 v229, v113, v229
	v_exp_f32_e32 v115, v99
	v_exp_f32_e32 v116, v116
	v_add_f32_e32 v97, v96, v97
	v_add_f32_e32 v99, v233, v229
	v_exp_f32_e32 v229, v100
	v_exp_f32_e32 v100, v117
	v_add_f32_e32 v97, v114, v97
	v_exp_f32_e32 v117, v101
	v_exp_f32_e32 v101, v118
	v_add_f32_e32 v97, v98, v97
	v_exp_f32_e32 v118, v102
	v_exp_f32_e32 v102, v119
	v_add_f32_e32 v99, v115, v99
	v_add_f32_e32 v97, v116, v97
	v_exp_f32_e32 v103, v103
	v_exp_f32_e32 v119, v120
	v_add_f32_e32 v99, v229, v99
	v_add_f32_e32 v97, v100, v97
	v_exp_f32_e32 v120, v104
	v_exp_f32_e32 v104, v121
	v_add_f32_e32 v99, v117, v99
	v_add_f32_e32 v97, v101, v97
	v_exp_f32_e32 v121, v105
	v_exp_f32_e32 v105, v122
	v_add_f32_e32 v99, v118, v99
	v_add_f32_e32 v97, v102, v97
	v_exp_f32_e32 v122, v106
	v_exp_f32_e32 v106, v123
	v_add_f32_e32 v99, v103, v99
	v_add_f32_e32 v97, v119, v97
	v_exp_f32_e32 v123, v107
	v_exp_f32_e32 v107, v124
	v_add_f32_e32 v99, v120, v99
	v_add_f32_e32 v97, v104, v97
	v_exp_f32_e32 v124, v108
	v_exp_f32_e32 v108, v125
	v_add_f32_e32 v99, v121, v99
	v_add_f32_e32 v97, v105, v97
	v_exp_f32_e32 v125, v109
	v_exp_f32_e32 v109, v126
	v_exp_f32_e32 v126, v110
	v_exp_f32_e32 v110, v127
	v_add_f32_e32 v99, v122, v99
	v_add_f32_e32 v97, v106, v97
	v_add_f32_e32 v99, v123, v99
	v_add_f32_e32 v97, v107, v97
	v_exp_f32_e32 v111, v111
	v_add_f32_e32 v99, v124, v99
	v_add_f32_e32 v97, v108, v97
	v_cvt_pk_bf16_f32 v105, v105, v106
	v_cvt_pk_bf16_f32 v106, v107, v108
	v_cvt_pk_bf16_f32 v108, v120, v121
	v_exp_f32_e32 v120, v80
	v_exp_f32_e32 v121, v64
	v_add_f32_e32 v99, v125, v99
	v_add_f32_e32 v97, v109, v97
	v_cvt_pk_bf16_f32 v107, v109, v110
	v_cvt_pk_bf16_f32 v109, v122, v123
	v_exp_f32_e32 v122, v81
	v_exp_f32_e32 v123, v65
	v_add_f32_e32 v99, v126, v99
	v_add_f32_e32 v97, v110, v97
	v_cvt_pk_bf16_f32 v110, v124, v125
	v_exp_f32_e32 v124, v82
	v_exp_f32_e32 v125, v66
	v_add_f32_e32 v99, v111, v99
	v_cvt_pk_bf16_f32 v111, v126, v111
	v_exp_f32_e32 v66, v83
	v_exp_f32_e32 v126, v67
	v_add_f32_e32 v64, 0, v120
	v_add_f32_e32 v65, 0, v121
	v_exp_f32_e32 v81, v84
	v_exp_f32_e32 v80, v68
	v_add_f32_e32 v64, v122, v64
	v_add_f32_e32 v65, v123, v65
	v_exp_f32_e32 v83, v85
	v_exp_f32_e32 v82, v69
	v_add_f32_e32 v64, v124, v64
	v_add_f32_e32 v67, v125, v65
	v_exp_f32_e32 v85, v86
	v_exp_f32_e32 v84, v70
	v_add_f32_e32 v97, v99, v97
	v_add_f32_e32 v65, v66, v64
	v_add_f32_e32 v64, v126, v67
	v_exp_f32_e32 v87, v87
	v_exp_f32_e32 v86, v71
	v_add_f32_e32 v222, v222, v97
	v_cvt_pk_bf16_f32 v96, v112, v96
	v_cvt_pk_bf16_f32 v97, v114, v98
	v_cvt_pk_bf16_f32 v98, v116, v100
	v_cvt_pk_bf16_f32 v100, v228, v113
	v_exp_f32_e32 v113, v88
	v_exp_f32_e32 v112, v72
	v_add_f32_e32 v64, v80, v64
	v_add_f32_e32 v65, v81, v65
	v_exp_f32_e32 v89, v89
	v_exp_f32_e32 v88, v73
	v_add_f32_e32 v64, v82, v64
	v_add_f32_e32 v65, v83, v65
	v_cvt_pk_bf16_f32 v99, v101, v102
	v_cvt_pk_bf16_f32 v101, v233, v115
	v_exp_f32_e32 v115, v90
	v_exp_f32_e32 v114, v74
	v_add_f32_e32 v64, v84, v64
	v_add_f32_e32 v65, v85, v65
	v_exp_f32_e32 v91, v91
	v_exp_f32_e32 v90, v75
	v_add_f32_e32 v64, v86, v64
	v_add_f32_e32 v65, v87, v65
	v_cvt_pk_bf16_f32 v102, v229, v117
	v_exp_f32_e32 v117, v92
	v_exp_f32_e32 v116, v76
	v_add_f32_e32 v64, v112, v64
	v_add_f32_e32 v65, v113, v65
	v_exp_f32_e32 v93, v93
	v_exp_f32_e32 v92, v77
	v_add_f32_e32 v64, v88, v64
	v_add_f32_e32 v65, v89, v65
	v_cvt_pk_bf16_f32 v103, v118, v103
	v_cvt_pk_bf16_f32 v104, v119, v104
	v_exp_f32_e32 v119, v94
	v_exp_f32_e32 v118, v78
	v_add_f32_e32 v64, v114, v64
	v_add_f32_e32 v65, v115, v65
	v_exp_f32_e32 v95, v95
	v_exp_f32_e32 v94, v79
	v_add_f32_e32 v64, v90, v64
	v_add_f32_e32 v65, v91, v65
	v_cvt_pk_bf16_f32 v67, v85, v87
	v_add_f32_e32 v64, v116, v64
	v_add_f32_e32 v65, v117, v65
	v_cvt_pk_bf16_f32 v68, v121, v123
	v_add_f32_e32 v64, v92, v64
	v_add_f32_e32 v65, v93, v65
	v_cvt_pk_bf16_f32 v69, v125, v126
	v_add_f32_e32 v64, v118, v64
	v_add_f32_e32 v65, v119, v65
	v_cvt_pk_bf16_f32 v70, v80, v82
	v_add_f32_e32 v64, v94, v64
	v_add_f32_e32 v65, v95, v65
	v_cvt_pk_bf16_f32 v71, v84, v86
	v_add_f32_e32 v64, v64, v65
	v_add_f32_e32 v227, v227, v64
	v_cvt_pk_bf16_f32 v64, v120, v122
	v_cvt_pk_bf16_f32 v65, v124, v66
	v_cvt_pk_bf16_f32 v66, v81, v83
	v_cvt_pk_bf16_f32 v72, v113, v89
	v_cvt_pk_bf16_f32 v73, v115, v91
	v_cvt_pk_bf16_f32 v74, v117, v93
	v_cvt_pk_bf16_f32 v75, v119, v95
	v_cvt_pk_bf16_f32 v76, v112, v88
	v_cvt_pk_bf16_f32 v77, v114, v90
	v_cvt_pk_bf16_f32 v78, v116, v92
	v_cvt_pk_bf16_f32 v79, v118, v94
	s_waitcnt lgkmcnt(0)
	v_mfma_f32_32x32x16_bf16 v[48:63], v[188:191], v[96:99], v[48:63]
	s_waitcnt vmcnt(0)
	s_add_i32 s2, s13, s10
	s_addk_i32 s45, 0x4000
	s_cmpk_lg_i32 s2, 0x83
	s_waitcnt vmcnt(0)
	s_barrier
	v_mfma_f32_32x32x16_bf16 v[32:47], v[184:187], v[96:99], v[32:47]
	v_mfma_f32_32x32x16_bf16 v[16:31], v[188:191], v[64:67], v[16:31]
	v_mfma_f32_32x32x16_bf16 v[0:15], v[184:187], v[64:67], v[0:15]
	v_mfma_f32_32x32x16_bf16 v[48:63], v[180:183], v[104:107], v[48:63]
	v_mfma_f32_32x32x16_bf16 v[32:47], v[176:179], v[104:107], v[32:47]
	v_mfma_f32_32x32x16_bf16 v[16:31], v[180:183], v[72:75], v[16:31]
	v_mfma_f32_32x32x16_bf16 v[0:15], v[176:179], v[72:75], v[0:15]
	v_mfma_f32_32x32x16_bf16 v[48:63], v[172:175], v[100:103], v[48:63]
	v_mfma_f32_32x32x16_bf16 v[32:47], v[168:171], v[100:103], v[32:47]
	v_mfma_f32_32x32x16_bf16 v[16:31], v[172:175], v[68:71], v[16:31]
	v_mfma_f32_32x32x16_bf16 v[0:15], v[168:171], v[68:71], v[0:15]
	v_mfma_f32_32x32x16_bf16 v[48:63], v[164:167], v[108:111], v[48:63]
	v_mfma_f32_32x32x16_bf16 v[32:47], v[160:163], v[108:111], v[32:47]
	v_mfma_f32_32x32x16_bf16 v[16:31], v[164:167], v[76:79], v[16:31]
	v_mfma_f32_32x32x16_bf16 v[0:15], v[160:163], v[76:79], v[0:15]
	s_cbranch_scc0 .LBB0_147

.LBB0_234:
	v_add_f32_e32 v143, 0, v143
	v_add_f32_e32 v150, 0, v150
	v_add_f32_e32 v143, v151, v143
	v_add_f32_e32 v150, v152, v150
	v_add_f32_e32 v143, v153, v143
	v_add_f32_e32 v150, v172, v150
	v_add_f32_e32 v143, v154, v143
	v_add_f32_e32 v150, v170, v150
	v_add_f32_e32 v143, v155, v143
	v_add_f32_e32 v150, v169, v150
	v_add_f32_e32 v143, v156, v143
	v_add_f32_e32 v150, v168, v150
	v_add_f32_e32 v143, v159, v143
	v_add_f32_e32 v150, v167, v150
	v_add_f32_e32 v143, v158, v143
	v_add_f32_e32 v150, v173, v150
	v_add_f32_e32 v143, v157, v143
	v_add_f32_e32 v150, v171, v150
	v_add_f32_e32 v143, v165, v143
	v_add_f32_e32 v150, v179, v150
	v_add_f32_e32 v143, v163, v143
	v_add_f32_e32 v150, v177, v150
	v_add_f32_e32 v143, v162, v143
	v_add_f32_e32 v150, v176, v150
	v_add_f32_e32 v143, v161, v143
	v_add_f32_e32 v150, v175, v150
	v_add_f32_e32 v143, v160, v143
	v_add_f32_e32 v150, v174, v150
	v_add_f32_e32 v143, v166, v143
	v_add_f32_e32 v150, v180, v150
	v_add_f32_e32 v143, v164, v143
	v_add_f32_e32 v150, v178, v150
	v_add_f32_e32 v143, v150, v143
	v_exp_f32_e32 v151, v80
	v_exp_f32_e32 v150, v64
	v_exp_f32_e32 v153, v81
	v_exp_f32_e32 v152, v65
	v_exp_f32_e32 v65, v82
	v_exp_f32_e32 v64, v66
	v_exp_f32_e32 v83, v83
	v_exp_f32_e32 v82, v67
	v_add_f32_e32 v66, 0, v150
	v_add_f32_e32 v67, 0, v151
	v_exp_f32_e32 v155, v84
	v_exp_f32_e32 v154, v68
	v_add_f32_e32 v66, v152, v66
	v_add_f32_e32 v67, v153, v67
	v_exp_f32_e32 v85, v85
	v_exp_f32_e32 v84, v69
	v_add_f32_e32 v66, v64, v66
	v_add_f32_e32 v67, v65, v67
	v_exp_f32_e32 v157, v86
	v_exp_f32_e32 v156, v70
	v_add_f32_e32 v66, v82, v66
	v_add_f32_e32 v67, v83, v67
	v_exp_f32_e32 v87, v87
	v_exp_f32_e32 v86, v71
	v_exp_f32_e32 v159, v88
	v_exp_f32_e32 v158, v72
	v_add_f32_e32 v66, v154, v66
	v_add_f32_e32 v67, v155, v67
	v_exp_f32_e32 v89, v89
	v_exp_f32_e32 v88, v73
	v_add_f32_e32 v66, v84, v66
	v_add_f32_e32 v67, v85, v67
	v_add_u32_e32 v81, s8, v139
	v_add_f32_e32 v66, v156, v66
	v_add_f32_e32 v67, v157, v67
	v_cvt_pk_bf16_f32 v71, v156, v86
	v_add_f32_e32 v66, v86, v66
	v_add_f32_e32 v67, v87, v67
	v_add_u32_e32 v86, v81, v148
	v_exp_f32_e32 v163, v92
	v_exp_f32_e32 v92, v77
	v_exp_f32_e32 v164, v78
	v_add_f32_e32 v66, v158, v66
	v_add_f32_e32 v67, v159, v67
	v_cvt_pk_bf16_f32 v77, v65, v83
	v_cvt_pk_bf16_f32 v78, v155, v85
	v_cvt_pk_bf16_f32 v69, v64, v82
	v_cvt_pk_bf16_f32 v70, v154, v84
	ds_read_b128 v[82:85], v86 offset:12288
	v_exp_f32_e32 v165, v94
	v_exp_f32_e32 v94, v79
	v_add_f32_e32 v66, v88, v66
	v_add_f32_e32 v67, v89, v67
	v_cvt_pk_bf16_f32 v79, v157, v87
	v_cvt_pk_bf16_f32 v72, v159, v89
	v_cvt_pk_bf16_f32 v64, v158, v88
	ds_read_b128 v[86:89], v86 offset:16384
	v_exp_f32_e32 v162, v76
	v_cvt_pk_bf16_f32 v76, v151, v153
	v_exp_f32_e32 v161, v90
	v_exp_f32_e32 v91, v91
	s_waitcnt lgkmcnt(0)
	v_mfma_f32_32x32x16_bf16 v[16:31], v[82:85], v[76:79], v[16:31]
	v_add_u32_e32 v82, v81, v147
	v_exp_f32_e32 v93, v93
	v_exp_f32_e32 v95, v95
	v_exp_f32_e32 v160, v74
	v_exp_f32_e32 v90, v75
	v_cvt_pk_bf16_f32 v73, v161, v91
	v_cvt_pk_bf16_f32 v74, v163, v93
	v_mfma_f32_32x32x16_bf16 v[0:15], v[86:89], v[76:79], v[0:15]
	ds_read_b128 v[76:79], v82 offset:12288
	ds_read_b128 v[82:85], v82 offset:16384
	v_cvt_pk_bf16_f32 v75, v165, v95
	v_cvt_pk_bf16_f32 v68, v150, v152
	v_add_f32_e64 v66, v160, v66
	v_add_f32_e64 v67, v161, v67
	v_cvt_pk_bf16_f32 v65, v160, v90
	v_add_f32_e32 v66, v90, v66
	v_add_f32_e32 v67, v91, v67
	s_waitcnt lgkmcnt(0)
	v_mfma_f32_32x32x16_bf16 v[16:31], v[76:79], v[72:75], v[16:31]
	v_add_u32_e32 v76, v81, v146
	v_add_f32_e64 v66, v162, v66
	v_add_f32_e64 v67, v163, v67
	v_add_f32_e32 v143, v149, v143
	v_add_f32_e64 v66, v92, v66
	v_add_f32_e64 v67, v93, v67
	s_cmp_lt_u32 s70, s10
	v_add_f32_e32 v66, v164, v66
	v_add_f32_e32 v67, v165, v67
	v_mfma_f32_32x32x16_bf16 v[0:15], v[82:85], v[72:75], v[0:15]
	ds_read_b128 v[72:75], v76 offset:12288
	ds_read_b128 v[76:79], v76 offset:16384
	v_add_f32_e64 v66, v94, v66
	v_add_f32_e64 v67, v95, v67
	v_add_f32_e32 v80, v66, v67
	v_cvt_pk_bf16_f32 v66, v162, v92
	v_cvt_pk_bf16_f32 v67, v164, v94
	s_waitcnt lgkmcnt(0)
	v_mfma_f32_32x32x16_bf16 v[16:31], v[72:75], v[68:71], v[16:31]
	v_add_u32_e32 v72, v81, v145
	v_add_f32_e32 v149, v80, v143
	v_mfma_f32_32x32x16_bf16 v[0:15], v[76:79], v[68:71], v[0:15]
	ds_read_b128 v[68:71], v72 offset:12288
	ds_read_b128 v[72:75], v72 offset:16384
	s_waitcnt vmcnt(0)
	s_waitcnt vmcnt(0) lgkmcnt(0)
	s_barrier
	v_mfma_f32_32x32x16_bf16 v[16:31], v[68:71], v[64:67], v[16:31]
	v_mfma_f32_32x32x16_bf16 v[0:15], v[72:75], v[64:67], v[0:15]
	s_cbranch_scc0 .LBB0_237
	s_mov_b32 s2, s17
	s_mov_b32 s17, s18
	s_mov_b32 s19, s70
	s_branch .LBB0_223
